# out-proj comp: second-half A fragments a1/a2 read ahead into freed quads v[90:97] (no mid-step LDS wait)
# speedup vs baseline: 1.0223x; 1.0035x over previous
.LBB0_80:
	ds_read_b128 v[114:117], v127 offset:16384
	ds_read_b128 v[118:121], v0
	ds_read_b128 v[166:169], v127 offset:18432
	ds_read_b128 v[170:173], v127 offset:20480
	ds_read_b128 v[174:177], v127 offset:22528
	ds_read_b128 v[238:241], v0 offset:2048
	ds_read_b128 v[242:245], v0 offset:4096
	ds_read_b128 v[246:249], v0 offset:6144
	s_andn2_b64 vcc, exec, s[38:39]
	s_waitcnt lgkmcnt(3)
	v_mfma_f32_16x16x32_bf16 v[78:81], v[114:117], v[118:121], v[78:81]
	ds_read_b128 v[230:233], v129 offset:16384
	ds_read_b128 v[234:237], v129 offset:22528
	ds_read_b128 v[90:93], v129 offset:18432
	ds_read_b128 v[94:97], v129 offset:20480
	v_mfma_f32_16x16x32_bf16 v[74:77], v[166:169], v[118:121], v[74:77]
	v_mfma_f32_16x16x32_bf16 v[70:73], v[170:173], v[118:121], v[70:73]
	v_mfma_f32_16x16x32_bf16 v[66:69], v[174:177], v[118:121], v[66:69]
	s_waitcnt lgkmcnt(6)
	v_mfma_f32_16x16x32_bf16 v[62:65], v[114:117], v[238:241], v[62:65]
	v_mfma_f32_16x16x32_bf16 v[58:61], v[166:169], v[238:241], v[58:61]
	v_mfma_f32_16x16x32_bf16 v[54:57], v[170:173], v[238:241], v[54:57]
	v_mfma_f32_16x16x32_bf16 v[50:53], v[174:177], v[238:241], v[50:53]
	ds_read_b128 v[238:241], v128 offset:2048
	s_waitcnt lgkmcnt(6)
	v_mfma_f32_16x16x32_bf16 v[218:221], v[114:117], v[242:245], v[46:49]
	v_mfma_f32_16x16x32_bf16 v[222:225], v[166:169], v[242:245], v[42:45]
	v_mfma_f32_16x16x32_bf16 v[226:229], v[170:173], v[242:245], v[38:41]
	v_mfma_f32_16x16x32_bf16 v[118:121], v[174:177], v[242:245], v[34:37]
	s_nop 2
	ds_read_b128 v[34:37], v128
	ds_read_b128 v[242:245], v128 offset:4096
	s_waitcnt lgkmcnt(7)
	v_mfma_f32_16x16x32_bf16 v[114:117], v[114:117], v[246:249], v[30:33]
	v_mfma_f32_16x16x32_bf16 v[166:169], v[166:169], v[246:249], v[26:29]
	v_mfma_f32_16x16x32_bf16 v[170:173], v[170:173], v[246:249], v[22:25]
	v_mfma_f32_16x16x32_bf16 v[18:21], v[174:177], v[246:249], v[18:21]
	ds_read_b128 v[246:249], v128 offset:6144
	s_waitcnt lgkmcnt(2)
	v_mfma_f32_16x16x32_bf16 v[22:25], v[230:233], v[34:37], v[78:81]
	v_mfma_f32_16x16x32_bf16 v[26:29], v[90:93], v[34:37], v[74:77]
	v_mfma_f32_16x16x32_bf16 v[30:33], v[94:97], v[34:37], v[70:73]
	v_mfma_f32_16x16x32_bf16 v[34:37], v[234:237], v[34:37], v[66:69]
	v_mfma_f32_16x16x32_bf16 v[38:41], v[230:233], v[238:241], v[62:65]
	v_mfma_f32_16x16x32_bf16 v[42:45], v[90:93], v[238:241], v[58:61]
	v_mfma_f32_16x16x32_bf16 v[46:49], v[94:97], v[238:241], v[54:57]
	v_mfma_f32_16x16x32_bf16 v[50:53], v[234:237], v[238:241], v[50:53]
	s_waitcnt lgkmcnt(1)
	v_mfma_f32_16x16x32_bf16 v[54:57], v[230:233], v[242:245], v[218:221]
	v_mfma_f32_16x16x32_bf16 v[58:61], v[90:93], v[242:245], v[222:225]
	v_mfma_f32_16x16x32_bf16 v[62:65], v[94:97], v[242:245], v[226:229]
	v_mfma_f32_16x16x32_bf16 v[66:69], v[234:237], v[242:245], v[118:121]
	s_waitcnt lgkmcnt(0)
	v_mfma_f32_16x16x32_bf16 v[70:73], v[230:233], v[246:249], v[114:117]
	v_mfma_f32_16x16x32_bf16 v[74:77], v[90:93], v[246:249], v[166:169]
	v_mfma_f32_16x16x32_bf16 v[78:81], v[94:97], v[246:249], v[170:173]
	v_mfma_f32_16x16x32_bf16 v[18:21], v[234:237], v[246:249], v[18:21]
	s_cbranch_vccnz .LBB0_82
	s_waitcnt vmcnt(0)
	ds_write_b16 v130, v2 offset:36864
	ds_write_b16_d16_hi v130, v2 offset:36992
	ds_write_b16 v131, v3 offset:36864
	ds_write_b16_d16_hi v132, v3 offset:36864
	ds_write_b16 v133, v4 offset:36864
	ds_write_b16_d16_hi v134, v4 offset:36864
	ds_write_b16 v135, v5 offset:36864
	ds_write_b16_d16_hi v136, v5 offset:36864
	ds_write_b16 v137, v6 offset:36864
	ds_write_b16_d16_hi v137, v6 offset:36992
	ds_write_b16 v138, v7 offset:36864
	ds_write_b16_d16_hi v139, v7 offset:36864
	ds_write_b16 v140, v8 offset:36864
	ds_write_b16_d16_hi v141, v8 offset:36864
	ds_write_b16 v142, v9 offset:36864
	ds_write_b16_d16_hi v143, v9 offset:36864
	ds_write_b16 v144, v10 offset:36864
	ds_write_b16_d16_hi v144, v10 offset:36992
	ds_write_b16 v145, v11 offset:36864
	ds_write_b16_d16_hi v154, v11 offset:36864
	ds_write_b16 v155, v12 offset:36864
	ds_write_b16_d16_hi v156, v12 offset:36864
	ds_write_b16 v157, v13 offset:36864
	ds_write_b16_d16_hi v158, v13 offset:36864
	ds_write_b16 v159, v14 offset:36864
	ds_write_b16_d16_hi v159, v14 offset:36992
	ds_write_b16 v160, v15 offset:36864
	ds_write_b16_d16_hi v161, v15 offset:36864
	ds_write_b16 v162, v16 offset:36864
	ds_write_b16_d16_hi v163, v16 offset:36864
	ds_write_b16 v164, v17 offset:36864
	ds_write_b16_d16_hi v165, v17 offset:36864

.LBB0_87:
	ds_read_b128 v[106:109], v127 offset:53248
	ds_read_b128 v[110:113], v0 offset:36864
	ds_read_b128 v[114:117], v127 offset:55296
	ds_read_b128 v[118:121], v127 offset:57344
	ds_read_b128 v[166:169], v127 offset:59392
	ds_read_b128 v[238:241], v0 offset:38912
	ds_read_b128 v[242:245], v0 offset:40960
	ds_read_b128 v[246:249], v0 offset:43008
	s_andn2_b64 vcc, exec, s[40:41]
	s_waitcnt lgkmcnt(3)
	v_mfma_f32_16x16x32_bf16 v[22:25], v[106:109], v[110:113], v[22:25]
	ds_read_b128 v[222:225], v129 offset:53248
	ds_read_b128 v[226:229], v129 offset:59392
	ds_read_b128 v[90:93], v129 offset:55296
	ds_read_b128 v[94:97], v129 offset:57344
	v_mfma_f32_16x16x32_bf16 v[26:29], v[114:117], v[110:113], v[26:29]
	v_mfma_f32_16x16x32_bf16 v[30:33], v[118:121], v[110:113], v[30:33]
	v_mfma_f32_16x16x32_bf16 v[34:37], v[166:169], v[110:113], v[34:37]
	s_waitcnt lgkmcnt(6)
	v_mfma_f32_16x16x32_bf16 v[38:41], v[106:109], v[238:241], v[38:41]
	v_mfma_f32_16x16x32_bf16 v[42:45], v[114:117], v[238:241], v[42:45]
	v_mfma_f32_16x16x32_bf16 v[46:49], v[118:121], v[238:241], v[46:49]
	v_mfma_f32_16x16x32_bf16 v[50:53], v[166:169], v[238:241], v[50:53]
	ds_read_b128 v[238:241], v128 offset:38912
	s_waitcnt lgkmcnt(6)
	v_mfma_f32_16x16x32_bf16 v[170:173], v[106:109], v[242:245], v[54:57]
	v_mfma_f32_16x16x32_bf16 v[174:177], v[114:117], v[242:245], v[58:61]
	v_mfma_f32_16x16x32_bf16 v[218:221], v[118:121], v[242:245], v[62:65]
	v_mfma_f32_16x16x32_bf16 v[110:113], v[166:169], v[242:245], v[66:69]
	s_nop 2
	ds_read_b128 v[54:57], v128 offset:36864
	ds_read_b128 v[242:245], v128 offset:40960
	s_waitcnt lgkmcnt(7)
	v_mfma_f32_16x16x32_bf16 v[106:109], v[106:109], v[246:249], v[70:73]
	v_mfma_f32_16x16x32_bf16 v[114:117], v[114:117], v[246:249], v[74:77]
	v_mfma_f32_16x16x32_bf16 v[118:121], v[118:121], v[246:249], v[78:81]
	v_mfma_f32_16x16x32_bf16 v[18:21], v[166:169], v[246:249], v[18:21]
	ds_read_b128 v[246:249], v128 offset:43008
	s_waitcnt lgkmcnt(2)
	v_mfma_f32_16x16x32_bf16 v[78:81], v[222:225], v[54:57], v[22:25]
	v_mfma_f32_16x16x32_bf16 v[74:77], v[90:93], v[54:57], v[26:29]
	v_mfma_f32_16x16x32_bf16 v[70:73], v[94:97], v[54:57], v[30:33]
	v_mfma_f32_16x16x32_bf16 v[66:69], v[226:229], v[54:57], v[34:37]
	v_mfma_f32_16x16x32_bf16 v[62:65], v[222:225], v[238:241], v[38:41]
	v_mfma_f32_16x16x32_bf16 v[58:61], v[90:93], v[238:241], v[42:45]
	v_mfma_f32_16x16x32_bf16 v[54:57], v[94:97], v[238:241], v[46:49]
	v_mfma_f32_16x16x32_bf16 v[50:53], v[226:229], v[238:241], v[50:53]
	s_waitcnt lgkmcnt(1)
	v_mfma_f32_16x16x32_bf16 v[34:37], v[226:229], v[242:245], v[110:113]
	v_mfma_f32_16x16x32_bf16 v[46:49], v[222:225], v[242:245], v[170:173]
	v_mfma_f32_16x16x32_bf16 v[42:45], v[90:93], v[242:245], v[174:177]
	v_mfma_f32_16x16x32_bf16 v[38:41], v[94:97], v[242:245], v[218:221]
	s_waitcnt lgkmcnt(0)
	v_mfma_f32_16x16x32_bf16 v[30:33], v[222:225], v[246:249], v[106:109]
	v_mfma_f32_16x16x32_bf16 v[26:29], v[90:93], v[246:249], v[114:117]
	v_mfma_f32_16x16x32_bf16 v[22:25], v[94:97], v[246:249], v[118:121]
	v_mfma_f32_16x16x32_bf16 v[18:21], v[226:229], v[246:249], v[18:21]
	s_cbranch_vccnz .LBB0_75
	s_waitcnt vmcnt(0)
	ds_write_b16 v130, v2
	ds_write_b16_d16_hi v130, v2 offset:128
	ds_write_b16 v131, v3
	ds_write_b16_d16_hi v132, v3
	ds_write_b16 v133, v4
	ds_write_b16_d16_hi v134, v4
	ds_write_b16 v135, v5
	ds_write_b16_d16_hi v136, v5
	ds_write_b16 v137, v6
	ds_write_b16_d16_hi v137, v6 offset:128
	ds_write_b16 v138, v7
	ds_write_b16_d16_hi v139, v7
	ds_write_b16 v140, v8
	ds_write_b16_d16_hi v141, v8
	ds_write_b16 v142, v9
	ds_write_b16_d16_hi v143, v9
	ds_write_b16 v144, v10
	ds_write_b16_d16_hi v144, v10 offset:128
	ds_write_b16 v145, v11
	ds_write_b16_d16_hi v154, v11
	ds_write_b16 v155, v12
	ds_write_b16_d16_hi v156, v12
	ds_write_b16 v157, v13
	ds_write_b16_d16_hi v158, v13
	ds_write_b16 v159, v14
	ds_write_b16_d16_hi v159, v14 offset:128
	ds_write_b16 v160, v15
	ds_write_b16_d16_hi v161, v15
	ds_write_b16 v162, v16
	ds_write_b16_d16_hi v163, v16
	ds_write_b16 v164, v17
	ds_write_b16_d16_hi v165, v17
	s_branch .LBB0_75
